# fox first-tile flag skips doomed fast attempt; G0 K loop static s_setprio 1 for waves 4-7
# speedup vs baseline: 1.0137x; 1.0003x over previous
; #define WAIT_V(n) asm volatile("s_waitcnt vmcnt(" #n ")" ::: "memory")
; #define BAR __builtin_amdgcn_s_barrier()
; template <int MODE>
; DI void gemm_phase(const Params& p, int layer, int hf, unsigned char* shmc, int tid) {
;     ...
;   for (int ui = 0; have; ++ui) {
;     const bool have_n = unit_next(ui + 1, gridDim.x, blockIdx.x, nM, nN, un);
;     const int brow = u.pm * BM, bcol = u.pn * BM;
;     f32x4 acc[2][2][4][2];
; #pragma unroll
;     for (int a = 0; a < 2; ++a)
; #pragma unroll
;       for (int b = 0; b < 2; ++b)
; #pragma unroll
;         for (int m = 0; m < 4; ++m)
; #pragma unroll
;           for (int n = 0; n < 2; ++n) acc[a][b][m][n] = (f32x4){0.f, 0.f, 0.f, 0.f};
;     const bf16_t* gA = (MODE == 0) ? A + (size_t)(brow >> 7) * nt * 4096 : A + (size_t)brow * lda; const bf16_t* gB = Bt + (size_t)(bcol >> 7) * nt * 4096;
;     ...
;     if (!pre) { STAGE_ALL(0, 0); STAGE_ALL(1, 1); }
;     STAGE_ALL(2, 2);
;     for (int kt = 0; kt < nt; ++kt) {
;       const int rem = nt - 1 - kt;
;       if (rem >= 2) WAIT_V(8); else if (rem == 1) WAIT_V(4); else WAIT_V(0);
;       BAR;
.Lg0_havepre:
	s_add_u32 m0, s29, 0x10000
	s_add_u32 s18, s98, 0x40000
	s_addc_u32 s19, s99, 0
	global_load_lds_dwordx4 v160, s[98:99]
	s_add_u32 m0, s29, 0x14000
	s_add_u32 s16, s100, 0x40000
	s_addc_u32 s17, s101, 0
	global_load_lds_dwordx4 v160, s[100:101]
	s_add_u32 m0, s29, 0x12000
	s_add_u32 s98, s98, 0x2000
	s_addc_u32 s99, s99, 0
	global_load_lds_dwordx4 v160, s[18:19]
	s_add_u32 m0, s29, 0x16000
	s_add_u32 s100, s100, 0x2000
	s_addc_u32 s101, s101, 0
	global_load_lds_dwordx4 v160, s[16:17]
	v_mov_b32_e32 v0, 0
	s_addc_u32 s15, s15, s17
	s_mov_b64 s[16:17], 0
	v_mov_b32_e32 v1, v0
	v_mov_b32_e32 v2, v0
	v_mov_b32_e32 v3, v0
	v_mov_b32_e32 v4, v0
	v_mov_b32_e32 v5, v0
	v_mov_b32_e32 v6, v0
	v_mov_b32_e32 v7, v0
	v_mov_b32_e32 v24, v0
	v_mov_b32_e32 v25, v0
	v_mov_b32_e32 v26, v0
	v_mov_b32_e32 v27, v0
	v_mov_b32_e32 v36, v0
	v_mov_b32_e32 v37, v0
	v_mov_b32_e32 v38, v0
	v_mov_b32_e32 v39, v0
	v_mov_b32_e32 v56, v0
	v_mov_b32_e32 v57, v0
	v_mov_b32_e32 v58, v0
	v_mov_b32_e32 v59, v0
	v_mov_b32_e32 v68, v0
	v_mov_b32_e32 v69, v0
	v_mov_b32_e32 v70, v0
	v_mov_b32_e32 v71, v0
	v_mov_b32_e32 v72, v0
	v_mov_b32_e32 v73, v0
	v_mov_b32_e32 v74, v0
	v_mov_b32_e32 v75, v0
	v_mov_b32_e32 v80, v0
	v_mov_b32_e32 v81, v0
	v_mov_b32_e32 v82, v0
	v_mov_b32_e32 v83, v0
	v_mov_b32_e32 v88, v0
	v_mov_b32_e32 v89, v0
	v_mov_b32_e32 v90, v0
	v_mov_b32_e32 v91, v0
	v_mov_b32_e32 v96, v0
	v_mov_b32_e32 v97, v0
	v_mov_b32_e32 v98, v0
	v_mov_b32_e32 v99, v0
	v_mov_b32_e32 v104, v0
	v_mov_b32_e32 v105, v0
	v_mov_b32_e32 v106, v0
	v_mov_b32_e32 v107, v0
	v_mov_b32_e32 v112, v0
	v_mov_b32_e32 v113, v0
	v_mov_b32_e32 v114, v0
	v_mov_b32_e32 v115, v0
	v_mov_b32_e32 v76, v0
	v_mov_b32_e32 v77, v0
	v_mov_b32_e32 v78, v0
	v_mov_b32_e32 v79, v0
	v_mov_b32_e32 v84, v0
	v_mov_b32_e32 v85, v0
	v_mov_b32_e32 v86, v0
	v_mov_b32_e32 v87, v0
	v_mov_b32_e32 v92, v0
	v_mov_b32_e32 v93, v0
	v_mov_b32_e32 v94, v0
	v_mov_b32_e32 v95, v0
	v_mov_b32_e32 v100, v0
	v_mov_b32_e32 v101, v0
	v_mov_b32_e32 v102, v0
	v_mov_b32_e32 v103, v0
	v_mov_b32_e32 v108, v0
	v_mov_b32_e32 v109, v0
	v_mov_b32_e32 v110, v0
	v_mov_b32_e32 v111, v0
	v_mov_b32_e32 v116, v0
	v_mov_b32_e32 v117, v0
	v_mov_b32_e32 v118, v0
	v_mov_b32_e32 v119, v0
	v_mov_b32_e32 v120, v0
	v_mov_b32_e32 v121, v0
	v_mov_b32_e32 v122, v0
	v_mov_b32_e32 v123, v0
	v_mov_b32_e32 v124, v0
	v_mov_b32_e32 v125, v0
	v_mov_b32_e32 v126, v0
	v_mov_b32_e32 v127, v0
	v_mov_b32_e32 v32, v0
	v_mov_b32_e32 v33, v0
	v_mov_b32_e32 v34, v0
	v_mov_b32_e32 v35, v0
	v_mov_b32_e32 v28, v0
	v_mov_b32_e32 v29, v0
	v_mov_b32_e32 v30, v0
	v_mov_b32_e32 v31, v0
	v_mov_b32_e32 v12, v0
	v_mov_b32_e32 v13, v0
	v_mov_b32_e32 v14, v0
	v_mov_b32_e32 v15, v0
	v_mov_b32_e32 v8, v0
	v_mov_b32_e32 v9, v0
	v_mov_b32_e32 v10, v0
	v_mov_b32_e32 v11, v0
	v_mov_b32_e32 v64, v0
	v_mov_b32_e32 v65, v0
	v_mov_b32_e32 v66, v0
	v_mov_b32_e32 v67, v0
	v_mov_b32_e32 v60, v0
	v_mov_b32_e32 v61, v0
	v_mov_b32_e32 v62, v0
	v_mov_b32_e32 v63, v0
	v_mov_b32_e32 v52, v0
	v_mov_b32_e32 v53, v0
	v_mov_b32_e32 v54, v0
	v_mov_b32_e32 v55, v0
	v_mov_b32_e32 v48, v0
	v_mov_b32_e32 v49, v0
	v_mov_b32_e32 v50, v0
	v_mov_b32_e32 v51, v0
	v_mov_b32_e32 v44, v0
	v_mov_b32_e32 v45, v0
	v_mov_b32_e32 v46, v0
	v_mov_b32_e32 v47, v0
	v_mov_b32_e32 v40, v0
	v_mov_b32_e32 v41, v0
	v_mov_b32_e32 v42, v0
	v_mov_b32_e32 v43, v0
	v_mov_b32_e32 v20, v0
	v_mov_b32_e32 v21, v0
	v_mov_b32_e32 v22, v0
	v_mov_b32_e32 v23, v0
	v_mov_b32_e32 v16, v0
	v_mov_b32_e32 v17, v0
	v_mov_b32_e32 v18, v0
	v_mov_b32_e32 v19, v0
	v_add_u32_e32 v191, 32, v178
	v_add_u32_e32 v192, 0x10020, v178
	v_add3_u32 v194, v179, v164, 32
	v_add_u32_e32 v202, 0x10000, v194
	v_readfirstlane_b32 s16, v172
	s_nop 3
	s_lshr_b32 s16, s16, 8
	s_cmp_lg_u32 s16, 0
	s_cbranch_scc0 .Lg0_noprio
	s_setprio 1
.Lg0_noprio:
	s_cmp_lg_u32 s28, 0
	s_mov_b32 s28, 0
	s_cbranch_scc1 .Lg0_wpre
	s_waitcnt vmcnt(8)
	s_branch .Lg0_wdone

; DI unsigned pk2(float lo, float hi) { unsigned r; asm volatile("v_cvt_pk_bf16_f32 %0, %1, %2" : "=v"(r) : "v"(lo), "v"(hi)); return r; }
; template <int MODE>
; DI void gemm_phase(const Params& p, int layer, int hf, unsigned char* shmc, int tid) {
;     ...
;     __syncthreads();
;     pre = false;
;     if (pre) {
;       gA = A + (size_t)((un.pm * BM) >> 7) * nt * 4096; gB = Bt + (size_t)((un.pn * BM) >> 7) * nt * 4096;
;       STAGE_ALL(0, 0); STAGE_ALL(1, 1);
;     }
;     const int row_b = brow + wr * 64 + fr, col_b = bcol + wc * 32 + fq * 4;
;     if (MODE == 0) {
;       if (u.pn < 26) {
;         bf16_t* proj = (bf16_t*)(wsb + WS_PROJ);
;         unsigned char* es = shmc + 65536;
; #pragma unroll
;         for (int ai = 0; ai < 2; ++ai) {
; #pragma unroll
;           for (int m = 0; m < 4; ++m) {
;             unsigned char* rp = es + (wr * 64 + m * 16 + fr) * 528 + (wc * 32 + fq * 4) * 2;
; #pragma unroll
;             for (int bj = 0; bj < 2; ++bj)
; #pragma unroll
;               for (int n = 0; n < 2; ++n) { const f32x4 v = acc[ai][bj][m][n]; uint2 w; w.x = pk2(v[0], v[1]); w.y = pk2(v[2], v[3]); *(uint2*)(rp + (bj * HALF + n * 16) * 2) = w; }
;           }
;           __syncthreads();
;           {
;             const int r0 = tid >> 5, ch = tid & 31;
; #pragma unroll
;             for (int i = 0; i < 8; ++i) {
;               const int row = r0 + 16 * i;
;               { typedef unsigned u32x4_t __attribute__((ext_vector_type(4))); const u32x4_t v_ = *(const u32x4_t*)(es + row * 528 + ch * 16); __builtin_nontemporal_store(v_, (u32x4_t*)(proj + (size_t)(brow + ai * HALF + row) * NP + bcol + ch * 8)); }
;             }
;           }
;           __syncthreads();
;         }
;       } else {
;         float* tail = (float*)(wsb + WS_TAIL);
;         float* sT = (float*)shmc;
;         if (wc == 0) {
; #pragma unroll
;           for (int ai = 0; ai < 2; ++ai)
; #pragma unroll
;             for (int m = 0; m < 4; ++m)
; #pragma unroll
;               for (int n = 0; n < 2; ++n) *(f32x4*)(sT + (ai * HALF + wr * 64 + m * 16 + fr) * 36 + n * 16 + fq * 4) = acc[ai][0][m][n];
;         }
.LBB0_168:
	s_mov_b32 s28, 0
	s_setprio 0
	s_lshl_b32 s18, s27, 8
	s_cmp_gt_i32 s26, 25
	s_mov_b64 s[10:11], -1
	s_waitcnt vmcnt(0)
	s_barrier
	s_cbranch_scc0 .LBB0_179
	s_and_saveexec_b64 s[10:11], s[0:1]
	s_cbranch_execz .LBB0_171
	ds_write_b128 v188, v[124:127]
	ds_write_b128 v188, v[120:123] offset:64
	ds_write_b128 v188, v[116:119] offset:2304
	ds_write_b128 v188, v[108:111] offset:2368
	ds_write_b128 v188, v[100:103] offset:4608
	ds_write_b128 v188, v[92:95] offset:4672
	ds_write_b128 v188, v[84:87] offset:6912
	ds_write_b128 v188, v[76:79] offset:6976
	ds_write_b128 v188, v[36:39] offset:18432
	ds_write_b128 v188, v[24:27] offset:18496
	ds_write_b128 v188, v[4:7] offset:20736
	ds_write_b128 v188, v[0:3] offset:20800
	ds_write_b128 v188, v[32:35] offset:23040
	ds_write_b128 v188, v[28:31] offset:23104
	ds_write_b128 v188, v[12:15] offset:25344
	ds_write_b128 v188, v[8:11] offset:25408

; DI void fox_unit(const Params& p, int hf, int bl, int fh, int qb, unsigned char* shm, int tid, bool dry = false) {
;     ...
;   f32x4 o[2][4];
; #pragma unroll
;   for (int mi = 0; mi < 2; ++mi)
; #pragma unroll
;     for (int d = 0; d < 4; ++d) o[mi][d] = (f32x4){0.f, 0.f, 0.f, 0.f};
;   float mrun[2] = {-1e30f, -1e30f}, lsum[2] = {0.f, 0.f};
;   const int skey = tid >> 3, sdg = tid & 7;
;   const int kst = ((skey >> 4) * 2 + (sdg >> 2)) * 1024 + ((((skey & 15) * 64) + (sdg & 3) * 16) ^ (((skey >> 3) & 1) << 5));
;   uint4 kreg, vreg; float freg = 0.f;
;   {
;     const size_t r = (size_t)(kt0 * 64 + skey) * NP;
;     kreg = *(const uint4*)(projb + r + C_FK + fh * 64 + sdg * 8); vreg = *(const uint4*)(projb + r + C_FV + fh * 64 + sdg * 8);
;     if (tid < 64) freg = (Fref - F[kt0 * 64 + tid]) * LOG2E;
;   }
;   {
;     bf16_t* sK = (bf16_t*)(shm + (kt0 & 1) * STG); bf16_t* sV = sK + 64 * 72; float* sFk = (float*)(sV + 64 * 72);
;     *(uint4*)((unsigned char*)sK + kst) = kreg; *(uint4*)(sV + skey * 72 + sdg * 8) = vreg;
;     if (tid < 64) sFk[tid] = freg;
;   }
;   __syncthreads();
.LBB0_481:
	v_mov_b32_e32 v129, 0
	s_andn2_b64 vcc, exec, s[4:5]
	v_mov_b32_e32 v128, v129
	v_mov_b32_e32 v143, v129
	v_mov_b32_e32 v142, v129
	v_mov_b32_e32 v145, v129
	v_mov_b32_e32 v144, v129
	v_mov_b32_e32 v139, v129
	v_mov_b32_e32 v138, v129
	v_mov_b32_e32 v141, v129
	v_mov_b32_e32 v140, v129
	v_mov_b32_e32 v135, v129
	v_mov_b32_e32 v134, v129
	v_mov_b32_e32 v137, v129
	v_mov_b32_e32 v136, v129
	v_mov_b32_e32 v131, v129
	v_mov_b32_e32 v130, v129
	v_mov_b32_e32 v133, v129
	v_mov_b32_e32 v132, v129
	v_mov_b32_e32 v123, v129
	v_mov_b32_e32 v122, v129
	v_mov_b32_e32 v125, v129
	v_mov_b32_e32 v124, v129
	v_mov_b32_e32 v119, v129
	v_mov_b32_e32 v118, v129
	v_mov_b32_e32 v121, v129
	v_mov_b32_e32 v120, v129
	v_mov_b32_e32 v115, v129
	v_mov_b32_e32 v114, v129
	v_mov_b32_e32 v117, v129
	v_mov_b32_e32 v116, v129
	v_mov_b32_e32 v111, v129
	v_mov_b32_e32 v110, v129
	v_mov_b32_e32 v113, v129
	v_mov_b32_e32 v112, v129
	s_cbranch_vccnz .LBB0_635
	v_or_b32_e32 v212, 31, v28
	v_lshlrev_b32_e32 v28, 2, v27
	v_lshlrev_b32_e32 v26, 6, v27
	v_and_b32_e32 v29, 32, v28
	v_bitop3_b32 v213, v26, v29, v24 bitop3:0x36
	v_lshrrev_b32_e32 v24, 2, v27
	v_or_b32_e32 v24, v209, v24
	v_mov_b32_e32 v112, 0
	v_and_b32_e32 v214, 12, v28
	v_mul_u32_u24_e32 v215, 0x90, v24
	v_add_u32_e32 v216, 64, v205
	v_add_u32_e32 v217, 64, v25
	v_readfirstlane_b32 s99, v205
	s_nop 3
	s_lshr_b32 s99, s99, 8
	v_mov_b32_e32 v219, 0xf149f2ca
	v_mov_b32_e32 v113, v112
	v_mov_b32_e32 v110, v112
	v_mov_b32_e32 v111, v112
	v_mov_b32_e32 v116, v112
	v_mov_b32_e32 v117, v112
	v_mov_b32_e32 v114, v112
	v_mov_b32_e32 v115, v112
	v_mov_b32_e32 v120, v112
	v_mov_b32_e32 v121, v112
	v_mov_b32_e32 v118, v112
	v_mov_b32_e32 v119, v112
	v_mov_b32_e32 v124, v112
	v_mov_b32_e32 v125, v112
	v_mov_b32_e32 v122, v112
	v_mov_b32_e32 v123, v112
	v_mov_b32_e32 v132, v112
	v_mov_b32_e32 v133, v112
	v_mov_b32_e32 v130, v112
	v_mov_b32_e32 v131, v112
	v_mov_b32_e32 v136, v112
	v_mov_b32_e32 v137, v112
	v_mov_b32_e32 v134, v112
	v_mov_b32_e32 v135, v112
	v_mov_b32_e32 v140, v112
	v_mov_b32_e32 v141, v112
	v_mov_b32_e32 v138, v112
	v_mov_b32_e32 v139, v112
	v_mov_b32_e32 v144, v112
	v_mov_b32_e32 v145, v112
	v_mov_b32_e32 v142, v112
	v_mov_b32_e32 v143, v112
	v_mov_b32_e32 v128, v112
	v_mov_b32_e32 v129, v112
	v_mov_b32_e32 v218, 0xf149f2ca
	s_mov_b32 s98, 0
	v_mov_b32_e32 v224, 0x7149f2ca
	v_mov_b32_e32 v225, v224
	v_mov_b32_e32 v226, v224
	v_mov_b32_e32 v227, v224
	v_mov_b32_e32 v228, v224
	v_mov_b32_e32 v229, v224
	v_mov_b32_e32 v230, v224
	v_mov_b32_e32 v231, v224

; template <bool DIAG>
; DI void fox_tile(const bf16_t* sK, const bf16_t* sV, const float* sFk, const bf16x8 (&qf)[2][2], f32x4 (&o)[2][4], float (&mrun)[2], float (&lsum)[2], int key0, int qg0, int fr, int fq, int lane) {
;   const float SC2 = 0.125f * LOG2E;
;   f32x4 s[2][4];
;   const int kof = (fr * 64 + fq * 16) ^ ((fr >> 3) << 5);
; #pragma unroll
;   for (int t = 0; t < 4; ++t) {
;     const bf16x8 k0 = *(const bf16x8*)((const unsigned char*)sK + (t * 2) * 1024 + kof), k1 = *(const bf16x8*)((const unsigned char*)sK + (t * 2 + 1) * 1024 + kof);
; #pragma unroll
;     for (int mi = 0; mi < 2; ++mi) { s[mi][t] = mmaT(qf[mi][0], k0, (f32x4){0.f, 0.f, 0.f, 0.f}); s[mi][t] = mmaT(qf[mi][1], k1, s[mi][t]); }
;   }
;   f32x4 fk[4];
; #pragma unroll
;   for (int t = 0; t < 4; ++t) fk[t] = *(const f32x4*)(sFk + 16 * t + 4 * fq);
;   __builtin_amdgcn_sched_barrier(0);
;   bf16x8 vf[2][4];
; #pragma unroll
;   for (int k2 = 0; k2 < 2; ++k2)
; #pragma unroll
;     for (int d = 0; d < 4; ++d) {
;       const bf16_t* a = sV + (32 * k2 + 4 * fq + (fr >> 2)) * 72 + 16 * d + 4 * (fr & 3);
;       const v4i16_t lo = tr_rd(a), hi = tr_rd(a + 16 * 72);
;       vf[k2][d] = __builtin_shufflevector(lo, hi, 0, 1, 2, 3, 4, 5, 6, 7);
;     }
;   __builtin_amdgcn_sched_barrier(0);
; #pragma unroll
;   for (int mi = 0; mi < 2; ++mi) {
;     float mx = -INFINITY;
; #pragma unroll
;     for (int t = 0; t < 4; ++t)
; #pragma unroll
;       for (int j = 0; j < 4; ++j) {
;         float x = __builtin_fmaf(s[mi][t][j], SC2, fk[t][j]);
; DI void fox_unit(const Params& p, int hf, int bl, int fh, int qb, unsigned char* shm, int tid, bool dry = false) {
;     ...
;   for (int kt = kt0; kt < nkt; ++kt) {
;     const int st = kt & 1;
;     if (kt + 1 < nkt) {
;       const size_t r = (size_t)((kt + 1) * 64 + skey) * NP;
;       kreg = *(const uint4*)(projb + r + C_FK + fh * 64 + sdg * 8); vreg = *(const uint4*)(projb + r + C_FV + fh * 64 + sdg * 8);
;       if (tid < 64) freg = (Fref - F[(kt + 1) * 64 + tid]) * LOG2E;
;     }
;     const bf16_t* sK = (const bf16_t*)(shm + st * STG); const bf16_t* sV = sK + 64 * 72; const float* sFk = (const float*)(sV + 64 * 72);
;     if (kt * 64 <= q0 + wid * 32 + 31) {
;       if (kt >= 4 * qb) fox_tile<true>(sK, sV, sFk, qf, o, mrun, lsum, kt * 64, qg0, fr, fq, lane);
;       else fox_tile<false>(sK, sV, sFk, qf, o, mrun, lsum, kt * 64, qg0, fr, fq, lane);
.LBB0_489:
	s_mul_i32 s4, s21, 0x4900
	s_add_i32 s4, s4, 32
	v_add_u32_e32 v24, s4, v213
	ds_read_b128 v[64:67], v24
	ds_read_b128 v[68:71], v24 offset:1024
	ds_read_b128 v[56:59], v24 offset:2048
	ds_read_b128 v[60:63], v24 offset:3072
	ds_read_b128 v[48:51], v24 offset:4096
	ds_read_b128 v[52:55], v24 offset:5120
	ds_read_b128 v[40:43], v24 offset:6144
	ds_read_b128 v[44:47], v24 offset:7168
	v_lshl_add_u32 v24, v209, 2, s4
	ds_read_b128 v[36:39], v24 offset:18432
	ds_read_b128 v[32:35], v24 offset:18496
	ds_read_b128 v[28:31], v24 offset:18560
	ds_read_b128 v[24:27], v24 offset:18624
	v_lshl_add_u32 v72, v214, 1, s4
	v_readfirstlane_b32 s100, v212
	s_add_i32 s101, s18, 94
	s_mov_b64 s[4:5], -1
	v_add_u32_e32 v221, v72, v215
	s_cmp_le_i32 s101, s100
	s_cbranch_scc1 .LBB0_491
	s_cmp_eq_u32 s98, 0
	s_cbranch_scc1 .Lfox1_dslow
	s_waitcnt lgkmcnt(11)
	v_mfma_f32_16x16x32_bf16 v[72:75], v[64:67], v[0:3], v[224:227]
	s_waitcnt lgkmcnt(10)
	v_mfma_f32_16x16x32_bf16 v[72:75], v[68:71], v[4:7], v[72:75]
	s_waitcnt lgkmcnt(9)
	v_mfma_f32_16x16x32_bf16 v[76:79], v[56:59], v[0:3], v[224:227]
	s_waitcnt lgkmcnt(8)
	v_mfma_f32_16x16x32_bf16 v[76:79], v[60:63], v[4:7], v[76:79]
	s_waitcnt lgkmcnt(7)
	v_mfma_f32_16x16x32_bf16 v[80:83], v[48:51], v[0:3], v[224:227]
	s_waitcnt lgkmcnt(6)
	v_mfma_f32_16x16x32_bf16 v[80:83], v[52:55], v[4:7], v[80:83]
	s_waitcnt lgkmcnt(5)
	v_mfma_f32_16x16x32_bf16 v[96:99], v[40:43], v[0:3], v[224:227]
	s_waitcnt lgkmcnt(4)
	v_mfma_f32_16x16x32_bf16 v[96:99], v[44:47], v[4:7], v[96:99]
	s_waitcnt lgkmcnt(0)
	v_add_u32_e32 v172, s18, v209
	v_sub_u32_e32 v172, v172, v206
	v_add_u32_e32 v176, -16, v172
	v_add_u32_e32 v173, 16, v172
	v_add_u32_e32 v177, 16, v176
	v_add_u32_e32 v174, 32, v172
	v_add_u32_e32 v178, 32, v176
	v_add_u32_e32 v175, 48, v172
	v_add_u32_e32 v179, 48, v176
	v_mfma_f32_16x16x32_bf16 v[84:87], v[64:67], v[8:11], v[228:231]
	v_mfma_f32_16x16x32_bf16 v[84:87], v[68:71], v[12:15], v[84:87]
	v_fmamk_f32 v72, v72, 0x3e38aa3b, v36
	v_fmamk_f32 v73, v73, 0x3e38aa3b, v37
	v_fmamk_f32 v74, v74, 0x3e38aa3b, v38
	v_fmamk_f32 v75, v75, 0x3e38aa3b, v39
	v_mfma_f32_16x16x32_bf16 v[88:91], v[56:59], v[8:11], v[228:231]
	v_mfma_f32_16x16x32_bf16 v[88:91], v[60:63], v[12:15], v[88:91]
	v_fmamk_f32 v76, v76, 0x3e38aa3b, v32
	v_fmamk_f32 v77, v77, 0x3e38aa3b, v33
	v_fmamk_f32 v78, v78, 0x3e38aa3b, v34
	v_fmamk_f32 v79, v79, 0x3e38aa3b, v35
	v_mfma_f32_16x16x32_bf16 v[92:95], v[48:51], v[8:11], v[228:231]
	v_mfma_f32_16x16x32_bf16 v[92:95], v[52:55], v[12:15], v[92:95]
	v_fmamk_f32 v80, v80, 0x3e38aa3b, v28
	v_fmamk_f32 v81, v81, 0x3e38aa3b, v29
	v_fmamk_f32 v82, v82, 0x3e38aa3b, v30
	v_fmamk_f32 v83, v83, 0x3e38aa3b, v31
	v_mfma_f32_16x16x32_bf16 v[164:167], v[40:43], v[8:11], v[228:231]
	v_mfma_f32_16x16x32_bf16 v[164:167], v[44:47], v[12:15], v[164:167]
	v_fmamk_f32 v96, v96, 0x3e38aa3b, v24
	v_fmamk_f32 v97, v97, 0x3e38aa3b, v25
	v_fmamk_f32 v98, v98, 0x3e38aa3b, v26
	v_fmamk_f32 v99, v99, 0x3e38aa3b, v27
	ds_read_b64_tr_b16 v[68:69], v221 offset:9216
	ds_read_b64_tr_b16 v[60:61], v221 offset:9248
	ds_read_b64_tr_b16 v[64:65], v221 offset:9280
	ds_read_b64_tr_b16 v[56:57], v221 offset:9312
	ds_read_b64_tr_b16 v[70:71], v221 offset:11520
	ds_read_b64_tr_b16 v[62:63], v221 offset:11552
	ds_read_b64_tr_b16 v[66:67], v221 offset:11584
	ds_read_b64_tr_b16 v[58:59], v221 offset:11616
	ds_read_b64_tr_b16 v[52:53], v221 offset:13824
	ds_read_b64_tr_b16 v[48:49], v221 offset:13856
	ds_read_b64_tr_b16 v[44:45], v221 offset:13888
	ds_read_b64_tr_b16 v[40:41], v221 offset:13920
	ds_read_b64_tr_b16 v[54:55], v221 offset:16128
	ds_read_b64_tr_b16 v[50:51], v221 offset:16160
	ds_read_b64_tr_b16 v[46:47], v221 offset:16192
	ds_read_b64_tr_b16 v[42:43], v221 offset:16224
	v_cmp_ge_i32_e32 vcc, 0, v172
	v_cmp_ge_i32_e64 s[4:5], -1, v172
	v_cmp_ge_i32_e64 s[100:101], -2, v172
	v_cndmask_b32_e32 v72, v200, v72, vcc
	v_cndmask_b32_e64 v73, v200, v73, s[4:5]
	v_cndmask_b32_e64 v74, v200, v74, s[100:101]
	v_cmp_ge_i32_e32 vcc, -3, v172
	v_cmp_ge_i32_e64 s[4:5], 0, v173
	v_cmp_ge_i32_e64 s[100:101], -1, v173
	v_cndmask_b32_e32 v75, v200, v75, vcc
	v_cndmask_b32_e64 v76, v200, v76, s[4:5]
	v_cndmask_b32_e64 v77, v200, v77, s[100:101]
	v_cmp_ge_i32_e32 vcc, -2, v173
	v_cmp_ge_i32_e64 s[4:5], -3, v173
	v_cmp_ge_i32_e64 s[100:101], 0, v174
	v_cndmask_b32_e32 v78, v200, v78, vcc
	v_cndmask_b32_e64 v79, v200, v79, s[4:5]
	v_cndmask_b32_e64 v80, v200, v80, s[100:101]
	v_cmp_ge_i32_e32 vcc, -1, v174
	v_cmp_ge_i32_e64 s[4:5], -2, v174
	v_cmp_ge_i32_e64 s[100:101], -3, v174
; DI unsigned pk2(float lo, float hi) { unsigned r; asm volatile("v_cvt_pk_bf16_f32 %0, %1, %2" : "=v"(r) : "v"(lo), "v"(hi)); return r; }
; DI float ex2(float x) { return __builtin_amdgcn_exp2f(x); }
; DI float shx(float v, int m, int lane) { return __int_as_float(__builtin_amdgcn_ds_bpermute((lane ^ m) << 2, __float_as_int(v))); }
; template <bool DIAG>
; DI void fox_tile(const bf16_t* sK, const bf16_t* sV, const float* sFk, const bf16x8 (&qf)[2][2], f32x4 (&o)[2][4], float (&mrun)[2], float (&lsum)[2], int key0, int qg0, int fr, int fq, int lane) {
;     ...
;   for (int mi = 0; mi < 2; ++mi) {
;     float mx = -INFINITY;
; #pragma unroll
;     for (int t = 0; t < 4; ++t)
; #pragma unroll
;       for (int j = 0; j < 4; ++j) {
;         float x = __builtin_fmaf(s[mi][t][j], SC2, fk[t][j]);
;         if (DIAG) { if (key0 + 16 * t + 4 * fq + j > qg0 + 16 * mi) x = -INFINITY; }
;         s[mi][t][j] = x; mx = fmaxf(mx, x);
;       }
;     mx = fmaxf(mx, shx(mx, 16, lane)); mx = fmaxf(mx, shx(mx, 32, lane));
;     const float mnew = fmaxf(mrun[mi], mx), alpha = ex2(mrun[mi] - mnew);
;     mrun[mi] = mnew;
;     float ps = 0.f;
; #pragma unroll
;     for (int t = 0; t < 4; ++t)
; #pragma unroll
;       for (int j = 0; j < 4; ++j) { const float pv = ex2(s[mi][t][j] - mnew); s[mi][t][j] = pv; ps += pv; }
;     lsum[mi] = lsum[mi] * alpha + ps;
; #pragma unroll
;     for (int d = 0; d < 4; ++d) o[mi][d] *= alpha;
;   }
; #pragma unroll
;   for (int k2 = 0; k2 < 2; ++k2) {
;     bf16x8 pa[2];
; #pragma unroll
;     for (int mi = 0; mi < 2; ++mi) pa[mi] = mk8(pk2(s[mi][2 * k2][0], s[mi][2 * k2][1]), pk2(s[mi][2 * k2][2], s[mi][2 * k2][3]), pk2(s[mi][2 * k2 + 1][0], s[mi][2 * k2 + 1][1]), pk2(s[mi][2 * k2 + 1][2], s[mi][2 * k2 + 1][3]));
	v_cndmask_b32_e32 v81, v200, v81, vcc
	v_cndmask_b32_e64 v82, v200, v82, s[4:5]
	v_cndmask_b32_e64 v83, v200, v83, s[100:101]
	v_cmp_ge_i32_e32 vcc, 0, v175
	v_cmp_ge_i32_e64 s[4:5], -1, v175
	v_cmp_ge_i32_e64 s[100:101], -2, v175
	v_cndmask_b32_e32 v96, v200, v96, vcc
	v_cndmask_b32_e64 v97, v200, v97, s[4:5]
	v_cndmask_b32_e64 v98, v200, v98, s[100:101]
	v_cmp_ge_i32_e32 vcc, -3, v175
	s_nop 1
	v_cndmask_b32_e32 v99, v200, v99, vcc
	v_exp_f32_e32 v72, v72
	v_exp_f32_e32 v73, v73
	v_exp_f32_e32 v74, v74
	v_exp_f32_e32 v75, v75
	v_exp_f32_e32 v76, v76
	v_exp_f32_e32 v77, v77
	v_exp_f32_e32 v78, v78
	v_exp_f32_e32 v79, v79
	v_exp_f32_e32 v80, v80
	v_exp_f32_e32 v81, v81
	v_exp_f32_e32 v82, v82
	v_exp_f32_e32 v83, v83
	v_exp_f32_e32 v96, v96
	v_exp_f32_e32 v97, v97
	v_exp_f32_e32 v98, v98
	v_exp_f32_e32 v99, v99
	v_fmamk_f32 v84, v84, 0x3e38aa3b, v36
	v_fmamk_f32 v85, v85, 0x3e38aa3b, v37
	v_fmamk_f32 v86, v86, 0x3e38aa3b, v38
	v_fmamk_f32 v87, v87, 0x3e38aa3b, v39
	v_fmamk_f32 v88, v88, 0x3e38aa3b, v32
	v_fmamk_f32 v89, v89, 0x3e38aa3b, v33
	v_fmamk_f32 v90, v90, 0x3e38aa3b, v34
	v_fmamk_f32 v91, v91, 0x3e38aa3b, v35
	v_fmamk_f32 v92, v92, 0x3e38aa3b, v28
	v_fmamk_f32 v93, v93, 0x3e38aa3b, v29
	v_fmamk_f32 v94, v94, 0x3e38aa3b, v30
	v_fmamk_f32 v95, v95, 0x3e38aa3b, v31
	v_fmamk_f32 v164, v164, 0x3e38aa3b, v24
	v_fmamk_f32 v165, v165, 0x3e38aa3b, v25
	v_fmamk_f32 v166, v166, 0x3e38aa3b, v26
	v_fmamk_f32 v167, v167, 0x3e38aa3b, v27
	v_cmp_ge_i32_e32 vcc, 0, v176
	v_cmp_ge_i32_e64 s[4:5], -1, v176
	v_cmp_ge_i32_e64 s[100:101], -2, v176
	v_cndmask_b32_e32 v84, v200, v84, vcc
	v_cndmask_b32_e64 v85, v200, v85, s[4:5]
	v_cndmask_b32_e64 v86, v200, v86, s[100:101]
	v_cmp_ge_i32_e32 vcc, -3, v176
	v_cmp_ge_i32_e64 s[4:5], 0, v177
	v_cmp_ge_i32_e64 s[100:101], -1, v177
	v_cndmask_b32_e32 v87, v200, v87, vcc
	v_cndmask_b32_e64 v88, v200, v88, s[4:5]
	v_cndmask_b32_e64 v89, v200, v89, s[100:101]
	v_cmp_ge_i32_e32 vcc, -2, v177
	v_cmp_ge_i32_e64 s[4:5], -3, v177
	v_cmp_ge_i32_e64 s[100:101], 0, v178
	v_cndmask_b32_e32 v90, v200, v90, vcc
	v_cndmask_b32_e64 v91, v200, v91, s[4:5]
	v_cndmask_b32_e64 v92, v200, v92, s[100:101]
	v_cmp_ge_i32_e32 vcc, -1, v178
	v_cmp_ge_i32_e64 s[4:5], -2, v178
	v_cmp_ge_i32_e64 s[100:101], -3, v178
	v_cndmask_b32_e32 v93, v200, v93, vcc
	v_cndmask_b32_e64 v94, v200, v94, s[4:5]
	v_cndmask_b32_e64 v95, v200, v95, s[100:101]
	v_cmp_ge_i32_e32 vcc, 0, v179
	v_cmp_ge_i32_e64 s[4:5], -1, v179
	v_cmp_ge_i32_e64 s[100:101], -2, v179
	v_cndmask_b32_e32 v164, v200, v164, vcc
	v_cndmask_b32_e64 v165, v200, v165, s[4:5]
	v_cndmask_b32_e64 v166, v200, v166, s[100:101]
	v_cmp_ge_i32_e32 vcc, -3, v179
	s_nop 1
	v_cndmask_b32_e32 v167, v200, v167, vcc
	v_add_f32_e32 v146, v72, v73
	v_add_f32_e32 v147, v74, v75
	v_add_f32_e32 v148, v76, v77
	v_add_f32_e32 v149, v78, v79
	v_add_f32_e32 v150, v80, v81
	v_add_f32_e32 v151, v82, v83
	v_add_f32_e32 v152, v96, v97
	v_add_f32_e32 v153, v98, v99
	v_add_f32_e32 v146, v146, v147
	v_add_f32_e32 v147, v148, v149
	v_add_f32_e32 v148, v150, v151
	v_add_f32_e32 v149, v152, v153
	v_add_f32_e32 v146, v146, v147
	v_add_f32_e32 v148, v148, v149
	v_add_f32_e32 v146, v146, v148
	v_exp_f32_e32 v84, v84
	v_exp_f32_e32 v85, v85
	v_exp_f32_e32 v86, v86
	v_exp_f32_e32 v87, v87
	v_exp_f32_e32 v88, v88
	v_exp_f32_e32 v89, v89
	v_exp_f32_e32 v90, v90
	v_exp_f32_e32 v91, v91
	v_exp_f32_e32 v92, v92
	v_exp_f32_e32 v93, v93
	v_exp_f32_e32 v94, v94
	v_exp_f32_e32 v95, v95
	v_exp_f32_e32 v164, v164
	v_exp_f32_e32 v165, v165
	v_exp_f32_e32 v166, v166
	v_exp_f32_e32 v167, v167
	v_add_f32_e32 v148, v84, v85
	v_add_f32_e32 v149, v86, v87
	v_add_f32_e32 v150, v88, v89
	v_add_f32_e32 v151, v90, v91
	v_add_f32_e32 v152, v92, v93
	v_add_f32_e32 v153, v94, v95
	v_add_f32_e32 v154, v164, v165
	v_add_f32_e32 v155, v166, v167
	v_add_f32_e32 v148, v148, v149
	v_add_f32_e32 v149, v150, v151
	v_add_f32_e32 v150, v152, v153
	v_add_f32_e32 v151, v154, v155
	v_add_f32_e32 v148, v148, v149
	v_add_f32_e32 v150, v150, v151
	v_add_f32_e32 v148, v148, v150
	v_max_f32_e32 v147, v146, v148
	v_cmp_lt_f32_e32 vcc, 0x69800000, v147
	s_cbranch_vccnz .Lfox1_dfallback
	v_add_f32_e32 v128, v128, v146
	v_add_f32_e32 v129, v129, v148
	v_cvt_pk_bf16_f32 v36, v72, v73
	v_cvt_pk_bf16_f32 v37, v74, v75
	v_cvt_pk_bf16_f32 v38, v76, v77
	v_cvt_pk_bf16_f32 v39, v78, v79
	v_cvt_pk_bf16_f32 v28, v80, v81
	v_cvt_pk_bf16_f32 v29, v82, v83
	v_cvt_pk_bf16_f32 v30, v96, v97
	v_cvt_pk_bf16_f32 v31, v98, v99
	s_cmp_eq_u32 s99, 0
	s_cbranch_scc1 .Lfox1_nm4
	s_barrier

; DI float ex2(float x) { return __builtin_amdgcn_exp2f(x); }
; template <bool DIAG>
; DI void fox_tile(const bf16_t* sK, const bf16_t* sV, const float* sFk, const bf16x8 (&qf)[2][2], f32x4 (&o)[2][4], float (&mrun)[2], float (&lsum)[2], int key0, int qg0, int fr, int fq, int lane) {
;   const float SC2 = 0.125f * LOG2E;
;   f32x4 s[2][4];
;   const int kof = (fr * 64 + fq * 16) ^ ((fr >> 3) << 5);
; #pragma unroll
;   for (int t = 0; t < 4; ++t) {
;     const bf16x8 k0 = *(const bf16x8*)((const unsigned char*)sK + (t * 2) * 1024 + kof), k1 = *(const bf16x8*)((const unsigned char*)sK + (t * 2 + 1) * 1024 + kof);
; #pragma unroll
;     for (int mi = 0; mi < 2; ++mi) { s[mi][t] = mmaT(qf[mi][0], k0, (f32x4){0.f, 0.f, 0.f, 0.f}); s[mi][t] = mmaT(qf[mi][1], k1, s[mi][t]); }
;   }
;   f32x4 fk[4];
; #pragma unroll
;   for (int t = 0; t < 4; ++t) fk[t] = *(const f32x4*)(sFk + 16 * t + 4 * fq);
;   __builtin_amdgcn_sched_barrier(0);
;   bf16x8 vf[2][4];
; #pragma unroll
;   for (int k2 = 0; k2 < 2; ++k2)
; #pragma unroll
;     for (int d = 0; d < 4; ++d) {
;       const bf16_t* a = sV + (32 * k2 + 4 * fq + (fr >> 2)) * 72 + 16 * d + 4 * (fr & 3);
;       const v4i16_t lo = tr_rd(a), hi = tr_rd(a + 16 * 72);
;       vf[k2][d] = __builtin_shufflevector(lo, hi, 0, 1, 2, 3, 4, 5, 6, 7);
;     }
;   __builtin_amdgcn_sched_barrier(0);
; #pragma unroll
;   for (int mi = 0; mi < 2; ++mi) {
;     float mx = -INFINITY;
; #pragma unroll
;     for (int t = 0; t < 4; ++t)
; #pragma unroll
;       for (int j = 0; j < 4; ++j) {
;         float x = __builtin_fmaf(s[mi][t][j], SC2, fk[t][j]);
;         if (DIAG) { if (key0 + 16 * t + 4 * fq + j > qg0 + 16 * mi) x = -INFINITY; }
;         s[mi][t][j] = x; mx = fmaxf(mx, x);
;       }
;     mx = fmaxf(mx, shx(mx, 16, lane)); mx = fmaxf(mx, shx(mx, 32, lane));
;     const float mnew = fmaxf(mrun[mi], mx), alpha = ex2(mrun[mi] - mnew);
;     mrun[mi] = mnew;
;     float ps = 0.f;
; #pragma unroll
;     for (int t = 0; t < 4; ++t)
; #pragma unroll
;       for (int j = 0; j < 4; ++j) { const float pv = ex2(s[mi][t][j] - mnew); s[mi][t][j] = pv; ps += pv; }
;     lsum[mi] = lsum[mi] * alpha + ps;
; #pragma unroll
;     for (int d = 0; d < 4; ++d) o[mi][d] *= alpha;
;   }
; #pragma unroll
;   for (int k2 = 0; k2 < 2; ++k2) {
;     bf16x8 pa[2];
; #pragma unroll
.LBB0_491:
	s_andn2_b64 vcc, exec, s[4:5]
	s_cbranch_vccnz .LBB0_493
	s_cmp_eq_u32 s98, 0
	s_cbranch_scc1 .Lfox1_slow
	s_waitcnt lgkmcnt(11)
	v_mfma_f32_16x16x32_bf16 v[72:75], v[64:67], v[0:3], v[224:227]
	s_waitcnt lgkmcnt(10)
	v_mfma_f32_16x16x32_bf16 v[72:75], v[68:71], v[4:7], v[72:75]
	s_waitcnt lgkmcnt(9)
	v_mfma_f32_16x16x32_bf16 v[76:79], v[56:59], v[0:3], v[224:227]
	s_waitcnt lgkmcnt(8)
	v_mfma_f32_16x16x32_bf16 v[76:79], v[60:63], v[4:7], v[76:79]
	s_waitcnt lgkmcnt(7)
	v_mfma_f32_16x16x32_bf16 v[80:83], v[48:51], v[0:3], v[224:227]
	s_waitcnt lgkmcnt(6)
	v_mfma_f32_16x16x32_bf16 v[80:83], v[52:55], v[4:7], v[80:83]
	s_waitcnt lgkmcnt(5)
	v_mfma_f32_16x16x32_bf16 v[96:99], v[40:43], v[0:3], v[224:227]
	s_waitcnt lgkmcnt(4)
	v_mfma_f32_16x16x32_bf16 v[96:99], v[44:47], v[4:7], v[96:99]
	s_waitcnt lgkmcnt(0)
	v_mfma_f32_16x16x32_bf16 v[84:87], v[64:67], v[8:11], v[228:231]
	v_mfma_f32_16x16x32_bf16 v[84:87], v[68:71], v[12:15], v[84:87]
	v_fmamk_f32 v72, v72, 0x3e38aa3b, v36
	v_fmamk_f32 v73, v73, 0x3e38aa3b, v37
	v_fmamk_f32 v74, v74, 0x3e38aa3b, v38
	v_fmamk_f32 v75, v75, 0x3e38aa3b, v39
	v_mfma_f32_16x16x32_bf16 v[88:91], v[56:59], v[8:11], v[228:231]
	v_mfma_f32_16x16x32_bf16 v[88:91], v[60:63], v[12:15], v[88:91]
	v_fmamk_f32 v76, v76, 0x3e38aa3b, v32
	v_fmamk_f32 v77, v77, 0x3e38aa3b, v33
	v_fmamk_f32 v78, v78, 0x3e38aa3b, v34
	v_fmamk_f32 v79, v79, 0x3e38aa3b, v35
	v_mfma_f32_16x16x32_bf16 v[92:95], v[48:51], v[8:11], v[228:231]
	v_mfma_f32_16x16x32_bf16 v[92:95], v[52:55], v[12:15], v[92:95]
	v_fmamk_f32 v80, v80, 0x3e38aa3b, v28
	v_fmamk_f32 v81, v81, 0x3e38aa3b, v29
	v_fmamk_f32 v82, v82, 0x3e38aa3b, v30
	v_fmamk_f32 v83, v83, 0x3e38aa3b, v31
	v_mfma_f32_16x16x32_bf16 v[164:167], v[40:43], v[8:11], v[228:231]
	v_mfma_f32_16x16x32_bf16 v[164:167], v[44:47], v[12:15], v[164:167]
	v_fmamk_f32 v96, v96, 0x3e38aa3b, v24
	v_fmamk_f32 v97, v97, 0x3e38aa3b, v25
	v_fmamk_f32 v98, v98, 0x3e38aa3b, v26
	v_fmamk_f32 v99, v99, 0x3e38aa3b, v27
	ds_read_b64_tr_b16 v[68:69], v221 offset:9216
	ds_read_b64_tr_b16 v[60:61], v221 offset:9248
	ds_read_b64_tr_b16 v[64:65], v221 offset:9280
	ds_read_b64_tr_b16 v[56:57], v221 offset:9312
	ds_read_b64_tr_b16 v[70:71], v221 offset:11520
	ds_read_b64_tr_b16 v[62:63], v221 offset:11552
	ds_read_b64_tr_b16 v[66:67], v221 offset:11584
	ds_read_b64_tr_b16 v[58:59], v221 offset:11616
	ds_read_b64_tr_b16 v[52:53], v221 offset:13824
	ds_read_b64_tr_b16 v[48:49], v221 offset:13856
	ds_read_b64_tr_b16 v[44:45], v221 offset:13888
	ds_read_b64_tr_b16 v[40:41], v221 offset:13920
	ds_read_b64_tr_b16 v[54:55], v221 offset:16128
	ds_read_b64_tr_b16 v[50:51], v221 offset:16160
	ds_read_b64_tr_b16 v[46:47], v221 offset:16192
	ds_read_b64_tr_b16 v[42:43], v221 offset:16224
	v_exp_f32_e32 v72, v72
	v_exp_f32_e32 v73, v73
	v_exp_f32_e32 v74, v74
	v_exp_f32_e32 v75, v75
	v_exp_f32_e32 v76, v76
	v_exp_f32_e32 v77, v77
	v_exp_f32_e32 v78, v78
	v_exp_f32_e32 v79, v79
	v_exp_f32_e32 v80, v80
	v_exp_f32_e32 v81, v81
	v_exp_f32_e32 v82, v82
	v_exp_f32_e32 v83, v83
	v_exp_f32_e32 v96, v96
	v_exp_f32_e32 v97, v97
	v_exp_f32_e32 v98, v98
	v_exp_f32_e32 v99, v99
	v_fmamk_f32 v84, v84, 0x3e38aa3b, v36
	v_fmamk_f32 v85, v85, 0x3e38aa3b, v37
	v_fmamk_f32 v86, v86, 0x3e38aa3b, v38
	v_fmamk_f32 v87, v87, 0x3e38aa3b, v39
	v_fmamk_f32 v88, v88, 0x3e38aa3b, v32
	v_fmamk_f32 v89, v89, 0x3e38aa3b, v33
	v_fmamk_f32 v90, v90, 0x3e38aa3b, v34
	v_fmamk_f32 v91, v91, 0x3e38aa3b, v35
	v_fmamk_f32 v92, v92, 0x3e38aa3b, v28
	v_fmamk_f32 v93, v93, 0x3e38aa3b, v29
	v_fmamk_f32 v94, v94, 0x3e38aa3b, v30
	v_fmamk_f32 v95, v95, 0x3e38aa3b, v31
	v_fmamk_f32 v164, v164, 0x3e38aa3b, v24
	v_fmamk_f32 v165, v165, 0x3e38aa3b, v25
	v_fmamk_f32 v166, v166, 0x3e38aa3b, v26
	v_fmamk_f32 v167, v167, 0x3e38aa3b, v27
	v_add_f32_e32 v146, v72, v73
	v_add_f32_e32 v147, v74, v75
	v_add_f32_e32 v148, v76, v77
	v_add_f32_e32 v149, v78, v79
	v_add_f32_e32 v150, v80, v81
	v_add_f32_e32 v151, v82, v83
	v_add_f32_e32 v152, v96, v97
	v_add_f32_e32 v153, v98, v99
	v_add_f32_e32 v146, v146, v147
	v_add_f32_e32 v147, v148, v149
	v_add_f32_e32 v148, v150, v151
	v_add_f32_e32 v149, v152, v153
	v_add_f32_e32 v146, v146, v147
	v_add_f32_e32 v148, v148, v149
	v_add_f32_e32 v146, v146, v148
	v_exp_f32_e32 v84, v84
	v_exp_f32_e32 v85, v85
	v_exp_f32_e32 v86, v86
	v_exp_f32_e32 v87, v87
	v_exp_f32_e32 v88, v88
	v_exp_f32_e32 v89, v89
	v_exp_f32_e32 v90, v90
	v_exp_f32_e32 v91, v91
	v_exp_f32_e32 v92, v92
	v_exp_f32_e32 v93, v93
	v_exp_f32_e32 v94, v94
	v_exp_f32_e32 v95, v95
	v_exp_f32_e32 v164, v164
	v_exp_f32_e32 v165, v165
	v_exp_f32_e32 v166, v166
	v_exp_f32_e32 v167, v167
	v_add_f32_e32 v148, v84, v85
	v_add_f32_e32 v149, v86, v87
	v_add_f32_e32 v150, v88, v89
	v_add_f32_e32 v151, v90, v91
	v_add_f32_e32 v152, v92, v93
	v_add_f32_e32 v153, v94, v95
	v_add_f32_e32 v154, v164, v165
	v_add_f32_e32 v155, v166, v167
	v_add_f32_e32 v148, v148, v149
	v_add_f32_e32 v149, v150, v151
	v_add_f32_e32 v150, v152, v153
	v_add_f32_e32 v151, v154, v155
	v_add_f32_e32 v148, v148, v149
	v_add_f32_e32 v150, v150, v151
	v_add_f32_e32 v148, v148, v150
	v_max_f32_e32 v147, v146, v148
	v_cmp_lt_f32_e32 vcc, 0x69800000, v147
	s_cbranch_vccnz .Lfox1_fallback
	v_add_f32_e32 v128, v128, v146
	v_add_f32_e32 v129, v129, v148
	v_cvt_pk_bf16_f32 v36, v72, v73
	v_cvt_pk_bf16_f32 v37, v74, v75
	v_cvt_pk_bf16_f32 v38, v76, v77
	v_cvt_pk_bf16_f32 v39, v78, v79
	v_cvt_pk_bf16_f32 v28, v80, v81
	v_cvt_pk_bf16_f32 v29, v82, v83
	v_cvt_pk_bf16_f32 v30, v96, v97
	v_cvt_pk_bf16_f32 v31, v98, v99
	s_cmp_eq_u32 s99, 0
	s_cbranch_scc1 .Lfox1_nm2
	s_barrier

; DI float ex2(float x) { return __builtin_amdgcn_exp2f(x); }
; DI float shx(float v, int m, int lane) { return __int_as_float(__builtin_amdgcn_ds_bpermute((lane ^ m) << 2, __float_as_int(v))); }
; template <bool DIAG>
; DI void fox_tile(const bf16_t* sK, const bf16_t* sV, const float* sFk, const bf16x8 (&qf)[2][2], f32x4 (&o)[2][4], float (&mrun)[2], float (&lsum)[2], int key0, int qg0, int fr, int fq, int lane) {
;     ...
;   for (int mi = 0; mi < 2; ++mi) {
;     float mx = -INFINITY;
; #pragma unroll
;     for (int t = 0; t < 4; ++t)
; #pragma unroll
;       for (int j = 0; j < 4; ++j) {
;         float x = __builtin_fmaf(s[mi][t][j], SC2, fk[t][j]);
;         if (DIAG) { if (key0 + 16 * t + 4 * fq + j > qg0 + 16 * mi) x = -INFINITY; }
;         s[mi][t][j] = x; mx = fmaxf(mx, x);
;       }
;     mx = fmaxf(mx, shx(mx, 16, lane)); mx = fmaxf(mx, shx(mx, 32, lane));
;     const float mnew = fmaxf(mrun[mi], mx), alpha = ex2(mrun[mi] - mnew);
;     mrun[mi] = mnew;
;     float ps = 0.f;
; #pragma unroll
;     for (int t = 0; t < 4; ++t)
; #pragma unroll
;       for (int j = 0; j < 4; ++j) { const float pv = ex2(s[mi][t][j] - mnew); s[mi][t][j] = pv; ps += pv; }
;     lsum[mi] = lsum[mi] * alpha + ps;
.Lfox1_nm0:
	s_waitcnt lgkmcnt(14)
	v_fmamk_f32 v72, v72, 0x3e38aa3b, v36
	v_fmamk_f32 v73, v73, 0x3e38aa3b, v37
	s_mov_b32 s4, 0xff800000
	v_max3_f32 v100, v72, s4, v73
	v_fmamk_f32 v74, v74, 0x3e38aa3b, v38
	v_fmamk_f32 v75, v75, 0x3e38aa3b, v39
	v_max3_f32 v100, v100, v74, v75
	v_fmamk_f32 v101, v76, 0x3e38aa3b, v32
	v_fmamk_f32 v77, v77, 0x3e38aa3b, v33
	v_max3_f32 v76, v100, v101, v77
	v_fmamk_f32 v100, v78, 0x3e38aa3b, v34
	v_fmamk_f32 v79, v79, 0x3e38aa3b, v35
	v_max3_f32 v76, v76, v100, v79
	v_fmamk_f32 v102, v80, 0x3e38aa3b, v28
	v_fmamk_f32 v81, v81, 0x3e38aa3b, v29
	v_max3_f32 v76, v76, v102, v81
	v_fmamk_f32 v103, v82, 0x3e38aa3b, v30
	v_fmamk_f32 v83, v83, 0x3e38aa3b, v31
	v_max3_f32 v76, v76, v103, v83
	v_fmamk_f32 v96, v96, 0x3e38aa3b, v24
	v_fmamk_f32 v97, v97, 0x3e38aa3b, v25
	v_max3_f32 v76, v76, v96, v97
	v_fmamk_f32 v98, v98, 0x3e38aa3b, v26
	v_fmamk_f32 v99, v99, 0x3e38aa3b, v27
	v_max3_f32 v76, v76, v98, v99
	ds_bpermute_b32 v78, v204, v76
	v_fmamk_f32 v36, v84, 0x3e38aa3b, v36
	v_fmamk_f32 v37, v85, 0x3e38aa3b, v37
	v_fmamk_f32 v38, v86, 0x3e38aa3b, v38
	v_fmac_f32_e32 v39, 0x3e38aa3b, v87
	s_waitcnt lgkmcnt(0)
	v_max_f32_e32 v78, v78, v78
	v_max_f32_e32 v76, v76, v78
	ds_bpermute_b32 v78, v169, v76
	v_fmamk_f32 v32, v88, 0x3e38aa3b, v32
	v_fmamk_f32 v33, v89, 0x3e38aa3b, v33
	v_fmamk_f32 v34, v90, 0x3e38aa3b, v34
	v_fmac_f32_e32 v35, 0x3e38aa3b, v91
	s_waitcnt lgkmcnt(0)
	v_max3_f32 v220, v219, v76, v78
	v_sub_f32_e32 v73, v73, v220
	v_exp_f32_e32 v76, v73
	v_sub_f32_e32 v73, v74, v220
	v_exp_f32_e32 v74, v73
	v_sub_f32_e32 v73, v75, v220
	v_exp_f32_e32 v78, v73
	v_sub_f32_e32 v73, v101, v220
	v_exp_f32_e32 v82, v73
	v_sub_f32_e32 v73, v77, v220
	v_exp_f32_e32 v80, v73
	v_sub_f32_e32 v73, v100, v220
	v_exp_f32_e32 v100, v73
	v_sub_f32_e32 v73, v79, v220
	v_exp_f32_e32 v104, v73
	v_sub_f32_e32 v73, v102, v220
	v_exp_f32_e32 v102, v73
	v_sub_f32_e32 v73, v81, v220
	v_exp_f32_e32 v106, v73
	v_sub_f32_e32 v73, v103, v220
	v_exp_f32_e32 v148, v73
	v_sub_f32_e32 v73, v83, v220
	v_exp_f32_e32 v146, v73
	v_sub_f32_e32 v73, v96, v220
	v_exp_f32_e32 v150, v73
	v_sub_f32_e32 v73, v97, v220
	v_exp_f32_e32 v154, v73
	v_sub_f32_e32 v73, v98, v220
	v_exp_f32_e32 v152, v73
	v_sub_f32_e32 v73, v99, v220
	v_exp_f32_e32 v158, v73
	v_max3_f32 v73, v36, s4, v37
	v_max3_f32 v73, v73, v38, v39
	v_max3_f32 v73, v73, v32, v33
	v_max3_f32 v73, v73, v34, v35
	v_fmamk_f32 v28, v92, 0x3e38aa3b, v28
	v_fmamk_f32 v29, v93, 0x3e38aa3b, v29
	v_max3_f32 v73, v73, v28, v29
	v_fmamk_f32 v30, v94, 0x3e38aa3b, v30
	v_fmac_f32_e32 v31, 0x3e38aa3b, v95
	v_max3_f32 v73, v73, v30, v31
	v_fmamk_f32 v24, v164, 0x3e38aa3b, v24
	v_fmamk_f32 v25, v165, 0x3e38aa3b, v25
	v_max3_f32 v73, v73, v24, v25
	v_fmamk_f32 v26, v166, 0x3e38aa3b, v26
	v_fmac_f32_e32 v27, 0x3e38aa3b, v167
	v_max3_f32 v73, v73, v26, v27
	ds_bpermute_b32 v75, v204, v73
	v_sub_f32_e32 v105, v219, v220
	v_exp_f32_e32 v156, v105
	v_sub_f32_e32 v72, v72, v220
	v_exp_f32_e32 v72, v72
	s_waitcnt lgkmcnt(0)
	v_max_f32_e32 v75, v75, v75
	v_max_f32_e32 v73, v73, v75
	ds_bpermute_b32 v75, v169, v73
	v_pk_mul_f32 v[86:87], v[144:145], v[156:157] op_sel_hi:[1,0]
	v_pk_mul_f32 v[84:85], v[142:143], v[156:157] op_sel_hi:[1,0]
	v_pk_mul_f32 v[90:91], v[140:141], v[156:157] op_sel_hi:[1,0]
	v_pk_mul_f32 v[88:89], v[138:139], v[156:157] op_sel_hi:[1,0]
	s_waitcnt lgkmcnt(0)
; DI unsigned pk2(float lo, float hi) { unsigned r; asm volatile("v_cvt_pk_bf16_f32 %0, %1, %2" : "=v"(r) : "v"(lo), "v"(hi)); return r; }
; DI float ex2(float x) { return __builtin_amdgcn_exp2f(x); }
; DI f32x4 mmaT(bf16x8 a_m, bf16x8 b_n, f32x4 c) { return __builtin_amdgcn_mfma_f32_16x16x32_bf16(b_n, a_m, c, 0, 0, 0); }
; template <bool DIAG>
; DI void fox_tile(const bf16_t* sK, const bf16_t* sV, const float* sFk, const bf16x8 (&qf)[2][2], f32x4 (&o)[2][4], float (&mrun)[2], float (&lsum)[2], int key0, int qg0, int fr, int fq, int lane) {
;     ...
;     const float mnew = fmaxf(mrun[mi], mx), alpha = ex2(mrun[mi] - mnew);
;     mrun[mi] = mnew;
;     float ps = 0.f;
; #pragma unroll
;     for (int t = 0; t < 4; ++t)
; #pragma unroll
;       for (int j = 0; j < 4; ++j) { const float pv = ex2(s[mi][t][j] - mnew); s[mi][t][j] = pv; ps += pv; }
;     lsum[mi] = lsum[mi] * alpha + ps;
; #pragma unroll
;     for (int d = 0; d < 4; ++d) o[mi][d] *= alpha;
;   }
; #pragma unroll
;   for (int k2 = 0; k2 < 2; ++k2) {
;     bf16x8 pa[2];
; #pragma unroll
;     for (int mi = 0; mi < 2; ++mi) pa[mi] = mk8(pk2(s[mi][2 * k2][0], s[mi][2 * k2][1]), pk2(s[mi][2 * k2][2], s[mi][2 * k2][3]), pk2(s[mi][2 * k2 + 1][0], s[mi][2 * k2 + 1][1]), pk2(s[mi][2 * k2 + 1][2], s[mi][2 * k2 + 1][3]));
; #pragma unroll
;     for (int d = 0; d < 4; ++d) {
; #pragma unroll
;       for (int mi = 0; mi < 2; ++mi) o[mi][d] = mmaT(pa[mi], vf[k2][d], o[mi][d]);
;     }
	v_max3_f32 v222, v218, v73, v75
	v_sub_f32_e32 v103, v218, v222
	v_pk_mul_f32 v[94:95], v[136:137], v[156:157] op_sel_hi:[1,0]
	v_pk_mul_f32 v[92:93], v[134:135], v[156:157] op_sel_hi:[1,0]
	v_pk_mul_f32 v[98:99], v[132:133], v[156:157] op_sel_hi:[1,0]
	v_pk_mul_f32 v[96:97], v[130:131], v[156:157] op_sel_hi:[1,0]
	v_exp_f32_e32 v157, v103
	v_sub_f32_e32 v32, v32, v222
	v_sub_f32_e32 v36, v36, v222
	v_exp_f32_e32 v83, v32
	v_sub_f32_e32 v32, v33, v222
	v_exp_f32_e32 v73, v36
	v_sub_f32_e32 v36, v37, v222
	v_exp_f32_e32 v81, v32
	v_sub_f32_e32 v32, v34, v222
	v_exp_f32_e32 v77, v36
	v_sub_f32_e32 v36, v38, v222
	v_exp_f32_e32 v101, v32
	v_sub_f32_e32 v32, v35, v222
	v_mov_b32_e32 v130, v157
	v_exp_f32_e32 v75, v36
	v_sub_f32_e32 v36, v39, v222
	v_exp_f32_e32 v105, v32
	v_sub_f32_e32 v28, v28, v222
	v_pk_mul_f32 v[34:35], v[124:125], v[130:131] op_sel_hi:[1,0]
	v_pk_mul_f32 v[32:33], v[122:123], v[130:131] op_sel_hi:[1,0]
	v_exp_f32_e32 v79, v36
	v_exp_f32_e32 v103, v28
	v_sub_f32_e32 v28, v29, v222
	v_cvt_pk_bf16_f32 v36, v72, v76
	v_cvt_pk_bf16_f32 v37, v74, v78
	v_cvt_pk_bf16_f32 v38, v82, v80
	v_cvt_pk_bf16_f32 v39, v100, v104
	v_cvt_pk_bf16_f32 v122, v73, v77
	v_cvt_pk_bf16_f32 v123, v75, v79
	v_cvt_pk_bf16_f32 v124, v83, v81
	v_cvt_pk_bf16_f32 v125, v101, v105
	v_sub_f32_e32 v24, v24, v222
	v_mfma_f32_16x16x32_bf16 v[32:35], v[68:71], v[122:125], v[32:35]
	v_exp_f32_e32 v107, v28
	v_sub_f32_e32 v28, v30, v222
	v_exp_f32_e32 v151, v24
	v_mfma_f32_16x16x32_bf16 v[84:87], v[68:71], v[36:39], v[84:87]
	v_sub_f32_e32 v68, v31, v222
	v_sub_f32_e32 v24, v25, v222
	v_exp_f32_e32 v149, v28
	v_mfma_f32_16x16x32_bf16 v[28:31], v[60:63], v[36:39], v[88:91]
	v_exp_f32_e32 v147, v68
	v_pk_mul_f32 v[70:71], v[120:121], v[130:131] op_sel_hi:[1,0]
	v_pk_mul_f32 v[68:69], v[118:119], v[130:131] op_sel_hi:[1,0]
	v_exp_f32_e32 v155, v24
	v_pk_mul_f32 v[90:91], v[116:117], v[130:131] op_sel_hi:[1,0]
	v_pk_mul_f32 v[88:89], v[114:115], v[130:131] op_sel_hi:[1,0]
	v_sub_f32_e32 v24, v26, v222
	v_mfma_f32_16x16x32_bf16 v[60:63], v[60:63], v[122:125], v[68:71]
	v_exp_f32_e32 v153, v24
	v_mfma_f32_16x16x32_bf16 v[68:71], v[64:67], v[36:39], v[92:95]
	v_mfma_f32_16x16x32_bf16 v[64:67], v[64:67], v[122:125], v[88:91]
	s_nop 2
	v_sub_f32_e32 v88, v27, v222
	v_mfma_f32_16x16x32_bf16 v[24:27], v[56:59], v[36:39], v[96:99]
	v_mul_f32_e64 v38, v112, v130
	v_mul_f32_e64 v39, v113, v130
	v_pk_mul_f32 v[36:37], v[110:111], v[130:131] op_sel_hi:[1,0]
	v_exp_f32_e32 v159, v88
	s_nop 0
	v_mfma_f32_16x16x32_bf16 v[36:39], v[56:59], v[122:125], v[36:39]
	v_cvt_pk_bf16_f32 v56, v102, v106
	v_cvt_pk_bf16_f32 v57, v148, v146
	v_cvt_pk_bf16_f32 v58, v150, v154
	v_cvt_pk_bf16_f32 v59, v152, v158
	v_cvt_pk_bf16_f32 v110, v103, v107
	v_cvt_pk_bf16_f32 v111, v149, v147
	v_cvt_pk_bf16_f32 v112, v151, v155
	v_cvt_pk_bf16_f32 v113, v153, v159
	s_nop 0
	v_mfma_f32_16x16x32_bf16 v[92:95], v[52:55], v[110:113], v[32:35]
	s_nop 2
	v_add_f32_e64 v32, v72, 0
	v_add_f32_e64 v33, v73, 0
	v_mfma_f32_16x16x32_bf16 v[88:91], v[52:55], v[56:59], v[84:87]
	v_add_f32_e64 v32, v76, v32
	v_add_f32_e64 v33, v77, v33
	v_mfma_f32_16x16x32_bf16 v[84:87], v[48:51], v[56:59], v[28:31]
	s_nop 2
	v_add_f32_e64 v28, v74, v32
	v_add_f32_e64 v29, v75, v33
	v_mfma_f32_16x16x32_bf16 v[96:99], v[48:51], v[110:113], v[60:63]
	v_add_f32_e64 v28, v78, v28
	v_add_f32_e64 v29, v79, v29
	v_pk_add_f32 v[28:29], v[82:83], v[28:29]
	v_mfma_f32_16x16x32_bf16 v[76:79], v[40:43], v[56:59], v[24:27]
	v_add_f32_e64 v28, v80, v28
	v_add_f32_e64 v29, v81, v29
	v_pk_add_f32 v[28:29], v[100:101], v[28:29]
	v_mfma_f32_16x16x32_bf16 v[80:83], v[44:47], v[56:59], v[68:71]
	v_add_f32_e64 v28, v104, v28
	v_add_f32_e64 v29, v105, v29
	v_pk_add_f32 v[28:29], v[102:103], v[28:29]
	v_mfma_f32_16x16x32_bf16 v[100:103], v[44:47], v[110:113], v[64:67]
	v_add_f32_e64 v28, v106, v28
	v_add_f32_e64 v29, v107, v29
	v_pk_add_f32 v[28:29], v[148:149], v[28:29]
	v_mfma_f32_16x16x32_bf16 v[72:75], v[40:43], v[110:113], v[36:39]
	v_add_f32_e64 v28, v146, v28
	v_add_f32_e64 v29, v147, v29
	v_pk_add_f32 v[28:29], v[150:151], v[28:29]
	s_nop 0
	v_pk_add_f32 v[28:29], v[154:155], v[28:29]
	s_nop 0
	v_pk_add_f32 v[24:25], v[152:153], v[28:29]
	s_nop 0
	v_pk_add_f32 v[24:25], v[158:159], v[24:25]
	s_nop 0
	v_pk_fma_f32 v[104:105], v[128:129], v[156:157], v[24:25]
	s_mov_b32 s98, 1
	v_mul_f32_e32 v224, 0xc0b17218, v220
	v_mul_f32_e32 v228, 0xc0b17218, v222
	v_mov_b32_e32 v225, v224
	v_mov_b32_e32 v229, v228
	v_mov_b32_e32 v226, v224
	v_mov_b32_e32 v230, v228
	v_mov_b32_e32 v227, v224
	v_mov_b32_e32 v231, v228

; template <bool DIAG>
; DI void fox_tile(const bf16_t* sK, const bf16_t* sV, const float* sFk, const bf16x8 (&qf)[2][2], f32x4 (&o)[2][4], float (&mrun)[2], float (&lsum)[2], int key0, int qg0, int fr, int fq, int lane) {
;   const float SC2 = 0.125f * LOG2E;
;   f32x4 s[2][4];
;   const int kof = (fr * 64 + fq * 16) ^ ((fr >> 3) << 5);
; #pragma unroll
;   for (int t = 0; t < 4; ++t) {
;     const bf16x8 k0 = *(const bf16x8*)((const unsigned char*)sK + (t * 2) * 1024 + kof), k1 = *(const bf16x8*)((const unsigned char*)sK + (t * 2 + 1) * 1024 + kof);
; #pragma unroll
;     for (int mi = 0; mi < 2; ++mi) { s[mi][t] = mmaT(qf[mi][0], k0, (f32x4){0.f, 0.f, 0.f, 0.f}); s[mi][t] = mmaT(qf[mi][1], k1, s[mi][t]); }
;   }
;   f32x4 fk[4];
; #pragma unroll
;   for (int t = 0; t < 4; ++t) fk[t] = *(const f32x4*)(sFk + 16 * t + 4 * fq);
;   __builtin_amdgcn_sched_barrier(0);
;   bf16x8 vf[2][4];
; #pragma unroll
;   for (int k2 = 0; k2 < 2; ++k2)
; #pragma unroll
;     for (int d = 0; d < 4; ++d) {
;       const bf16_t* a = sV + (32 * k2 + 4 * fq + (fr >> 2)) * 72 + 16 * d + 4 * (fr & 3);
;       const v4i16_t lo = tr_rd(a), hi = tr_rd(a + 16 * 72);
;       vf[k2][d] = __builtin_shufflevector(lo, hi, 0, 1, 2, 3, 4, 5, 6, 7);
;     }
;   __builtin_amdgcn_sched_barrier(0);
; #pragma unroll
;   for (int mi = 0; mi < 2; ++mi) {
;     float mx = -INFINITY;
; #pragma unroll
;     for (int t = 0; t < 4; ++t)
; #pragma unroll
;       for (int j = 0; j < 4; ++j) {
;         float x = __builtin_fmaf(s[mi][t][j], SC2, fk[t][j]);
; DI void fox_unit(const Params& p, int hf, int bl, int fh, int qb, unsigned char* shm, int tid, bool dry = false) {
;     ...
;   for (int kt = kt0; kt < nkt; ++kt) {
;     const int st = kt & 1;
;     if (kt + 1 < nkt) {
;       const size_t r = (size_t)((kt + 1) * 64 + skey) * NP;
;       kreg = *(const uint4*)(projb + r + C_FK + fh * 64 + sdg * 8); vreg = *(const uint4*)(projb + r + C_FV + fh * 64 + sdg * 8);
;       if (tid < 64) freg = (Fref - F[(kt + 1) * 64 + tid]) * LOG2E;
;     }
;     const bf16_t* sK = (const bf16_t*)(shm + st * STG); const bf16_t* sV = sK + 64 * 72; const float* sFk = (const float*)(sV + 64 * 72);
;     if (kt * 64 <= q0 + wid * 32 + 31) {
;       if (kt >= 4 * qb) fox_tile<true>(sK, sV, sFk, qf, o, mrun, lsum, kt * 64, qg0, fr, fq, lane);
;       else fox_tile<false>(sK, sV, sFk, qf, o, mrun, lsum, kt * 64, qg0, fr, fq, lane);
.LBB0_609:
	s_mul_i32 s4, s20, 0x4900
	s_add_i32 s4, s4, 32
	v_add_u32_e32 v24, s4, v213
	ds_read_b128 v[64:67], v24
	ds_read_b128 v[68:71], v24 offset:1024
	ds_read_b128 v[56:59], v24 offset:2048
	ds_read_b128 v[60:63], v24 offset:3072
	ds_read_b128 v[48:51], v24 offset:4096
	ds_read_b128 v[52:55], v24 offset:5120
	ds_read_b128 v[40:43], v24 offset:6144
	ds_read_b128 v[44:47], v24 offset:7168
	v_lshl_add_u32 v24, v209, 2, s4
	ds_read_b128 v[36:39], v24 offset:18432
	ds_read_b128 v[32:35], v24 offset:18496
	ds_read_b128 v[28:31], v24 offset:18560
	ds_read_b128 v[24:27], v24 offset:18624
	v_lshl_add_u32 v72, v214, 1, s4
	v_readfirstlane_b32 s100, v212
	s_add_i32 s101, s17, 94
	s_mov_b64 s[4:5], -1
	v_add_u32_e32 v221, v72, v215
	s_cmp_le_i32 s101, s100
	s_cbranch_scc1 .LBB0_611
	s_cmp_eq_u32 s98, 0
	s_cbranch_scc1 .Lfox2_dslow
	s_waitcnt lgkmcnt(11)
	v_mfma_f32_16x16x32_bf16 v[72:75], v[64:67], v[0:3], v[224:227]
	s_waitcnt lgkmcnt(10)
	v_mfma_f32_16x16x32_bf16 v[72:75], v[68:71], v[4:7], v[72:75]
	s_waitcnt lgkmcnt(9)
	v_mfma_f32_16x16x32_bf16 v[76:79], v[56:59], v[0:3], v[224:227]
	s_waitcnt lgkmcnt(8)
	v_mfma_f32_16x16x32_bf16 v[76:79], v[60:63], v[4:7], v[76:79]
	s_waitcnt lgkmcnt(7)
	v_mfma_f32_16x16x32_bf16 v[80:83], v[48:51], v[0:3], v[224:227]
	s_waitcnt lgkmcnt(6)
	v_mfma_f32_16x16x32_bf16 v[80:83], v[52:55], v[4:7], v[80:83]
	s_waitcnt lgkmcnt(5)
	v_mfma_f32_16x16x32_bf16 v[96:99], v[40:43], v[0:3], v[224:227]
	s_waitcnt lgkmcnt(4)
	v_mfma_f32_16x16x32_bf16 v[96:99], v[44:47], v[4:7], v[96:99]
	s_waitcnt lgkmcnt(0)
	v_add_u32_e32 v172, s17, v209
	v_sub_u32_e32 v172, v172, v206
	v_add_u32_e32 v176, -16, v172
	v_add_u32_e32 v173, 16, v172
	v_add_u32_e32 v177, 16, v176
	v_add_u32_e32 v174, 32, v172
	v_add_u32_e32 v178, 32, v176
	v_add_u32_e32 v175, 48, v172
	v_add_u32_e32 v179, 48, v176
	v_mfma_f32_16x16x32_bf16 v[84:87], v[64:67], v[8:11], v[228:231]
	v_mfma_f32_16x16x32_bf16 v[84:87], v[68:71], v[12:15], v[84:87]
	v_fmamk_f32 v72, v72, 0x3e38aa3b, v36
	v_fmamk_f32 v73, v73, 0x3e38aa3b, v37
	v_fmamk_f32 v74, v74, 0x3e38aa3b, v38
	v_fmamk_f32 v75, v75, 0x3e38aa3b, v39
	v_mfma_f32_16x16x32_bf16 v[88:91], v[56:59], v[8:11], v[228:231]
	v_mfma_f32_16x16x32_bf16 v[88:91], v[60:63], v[12:15], v[88:91]
	v_fmamk_f32 v76, v76, 0x3e38aa3b, v32
	v_fmamk_f32 v77, v77, 0x3e38aa3b, v33
	v_fmamk_f32 v78, v78, 0x3e38aa3b, v34
	v_fmamk_f32 v79, v79, 0x3e38aa3b, v35
	v_mfma_f32_16x16x32_bf16 v[92:95], v[48:51], v[8:11], v[228:231]
	v_mfma_f32_16x16x32_bf16 v[92:95], v[52:55], v[12:15], v[92:95]
	v_fmamk_f32 v80, v80, 0x3e38aa3b, v28
	v_fmamk_f32 v81, v81, 0x3e38aa3b, v29
	v_fmamk_f32 v82, v82, 0x3e38aa3b, v30
	v_fmamk_f32 v83, v83, 0x3e38aa3b, v31
	v_mfma_f32_16x16x32_bf16 v[164:167], v[40:43], v[8:11], v[228:231]
	v_mfma_f32_16x16x32_bf16 v[164:167], v[44:47], v[12:15], v[164:167]
	v_fmamk_f32 v96, v96, 0x3e38aa3b, v24
	v_fmamk_f32 v97, v97, 0x3e38aa3b, v25
	v_fmamk_f32 v98, v98, 0x3e38aa3b, v26
	v_fmamk_f32 v99, v99, 0x3e38aa3b, v27
	ds_read_b64_tr_b16 v[68:69], v221 offset:9216
	ds_read_b64_tr_b16 v[60:61], v221 offset:9248
	ds_read_b64_tr_b16 v[64:65], v221 offset:9280
	ds_read_b64_tr_b16 v[56:57], v221 offset:9312
	ds_read_b64_tr_b16 v[70:71], v221 offset:11520
	ds_read_b64_tr_b16 v[62:63], v221 offset:11552
	ds_read_b64_tr_b16 v[66:67], v221 offset:11584
	ds_read_b64_tr_b16 v[58:59], v221 offset:11616
	ds_read_b64_tr_b16 v[52:53], v221 offset:13824
	ds_read_b64_tr_b16 v[48:49], v221 offset:13856
	ds_read_b64_tr_b16 v[44:45], v221 offset:13888
	ds_read_b64_tr_b16 v[40:41], v221 offset:13920
	ds_read_b64_tr_b16 v[54:55], v221 offset:16128
	ds_read_b64_tr_b16 v[50:51], v221 offset:16160
	ds_read_b64_tr_b16 v[46:47], v221 offset:16192
	ds_read_b64_tr_b16 v[42:43], v221 offset:16224
	v_cmp_ge_i32_e32 vcc, 0, v172
	v_cmp_ge_i32_e64 s[4:5], -1, v172
	v_cmp_ge_i32_e64 s[100:101], -2, v172
	v_cndmask_b32_e32 v72, v200, v72, vcc
	v_cndmask_b32_e64 v73, v200, v73, s[4:5]
	v_cndmask_b32_e64 v74, v200, v74, s[100:101]
	v_cmp_ge_i32_e32 vcc, -3, v172
	v_cmp_ge_i32_e64 s[4:5], 0, v173
	v_cmp_ge_i32_e64 s[100:101], -1, v173
	v_cndmask_b32_e32 v75, v200, v75, vcc
	v_cndmask_b32_e64 v76, v200, v76, s[4:5]
	v_cndmask_b32_e64 v77, v200, v77, s[100:101]
	v_cmp_ge_i32_e32 vcc, -2, v173
	v_cmp_ge_i32_e64 s[4:5], -3, v173
	v_cmp_ge_i32_e64 s[100:101], 0, v174
	v_cndmask_b32_e32 v78, v200, v78, vcc
	v_cndmask_b32_e64 v79, v200, v79, s[4:5]
	v_cndmask_b32_e64 v80, v200, v80, s[100:101]
	v_cmp_ge_i32_e32 vcc, -1, v174
	v_cmp_ge_i32_e64 s[4:5], -2, v174
	v_cmp_ge_i32_e64 s[100:101], -3, v174
; DI unsigned pk2(float lo, float hi) { unsigned r; asm volatile("v_cvt_pk_bf16_f32 %0, %1, %2" : "=v"(r) : "v"(lo), "v"(hi)); return r; }
; DI float ex2(float x) { return __builtin_amdgcn_exp2f(x); }
; DI float shx(float v, int m, int lane) { return __int_as_float(__builtin_amdgcn_ds_bpermute((lane ^ m) << 2, __float_as_int(v))); }
; template <bool DIAG>
; DI void fox_tile(const bf16_t* sK, const bf16_t* sV, const float* sFk, const bf16x8 (&qf)[2][2], f32x4 (&o)[2][4], float (&mrun)[2], float (&lsum)[2], int key0, int qg0, int fr, int fq, int lane) {
;     ...
;   for (int mi = 0; mi < 2; ++mi) {
;     float mx = -INFINITY;
; #pragma unroll
;     for (int t = 0; t < 4; ++t)
; #pragma unroll
;       for (int j = 0; j < 4; ++j) {
;         float x = __builtin_fmaf(s[mi][t][j], SC2, fk[t][j]);
;         if (DIAG) { if (key0 + 16 * t + 4 * fq + j > qg0 + 16 * mi) x = -INFINITY; }
;         s[mi][t][j] = x; mx = fmaxf(mx, x);
;       }
;     mx = fmaxf(mx, shx(mx, 16, lane)); mx = fmaxf(mx, shx(mx, 32, lane));
;     const float mnew = fmaxf(mrun[mi], mx), alpha = ex2(mrun[mi] - mnew);
;     mrun[mi] = mnew;
;     float ps = 0.f;
; #pragma unroll
;     for (int t = 0; t < 4; ++t)
; #pragma unroll
;       for (int j = 0; j < 4; ++j) { const float pv = ex2(s[mi][t][j] - mnew); s[mi][t][j] = pv; ps += pv; }
;     lsum[mi] = lsum[mi] * alpha + ps;
; #pragma unroll
;     for (int d = 0; d < 4; ++d) o[mi][d] *= alpha;
;   }
; #pragma unroll
;   for (int k2 = 0; k2 < 2; ++k2) {
;     bf16x8 pa[2];
; #pragma unroll
;     for (int mi = 0; mi < 2; ++mi) pa[mi] = mk8(pk2(s[mi][2 * k2][0], s[mi][2 * k2][1]), pk2(s[mi][2 * k2][2], s[mi][2 * k2][3]), pk2(s[mi][2 * k2 + 1][0], s[mi][2 * k2 + 1][1]), pk2(s[mi][2 * k2 + 1][2], s[mi][2 * k2 + 1][3]));
	v_cndmask_b32_e32 v81, v200, v81, vcc
	v_cndmask_b32_e64 v82, v200, v82, s[4:5]
	v_cndmask_b32_e64 v83, v200, v83, s[100:101]
	v_cmp_ge_i32_e32 vcc, 0, v175
	v_cmp_ge_i32_e64 s[4:5], -1, v175
	v_cmp_ge_i32_e64 s[100:101], -2, v175
	v_cndmask_b32_e32 v96, v200, v96, vcc
	v_cndmask_b32_e64 v97, v200, v97, s[4:5]
	v_cndmask_b32_e64 v98, v200, v98, s[100:101]
	v_cmp_ge_i32_e32 vcc, -3, v175
	s_nop 1
	v_cndmask_b32_e32 v99, v200, v99, vcc
	v_exp_f32_e32 v72, v72
	v_exp_f32_e32 v73, v73
	v_exp_f32_e32 v74, v74
	v_exp_f32_e32 v75, v75
	v_exp_f32_e32 v76, v76
	v_exp_f32_e32 v77, v77
	v_exp_f32_e32 v78, v78
	v_exp_f32_e32 v79, v79
	v_exp_f32_e32 v80, v80
	v_exp_f32_e32 v81, v81
	v_exp_f32_e32 v82, v82
	v_exp_f32_e32 v83, v83
	v_exp_f32_e32 v96, v96
	v_exp_f32_e32 v97, v97
	v_exp_f32_e32 v98, v98
	v_exp_f32_e32 v99, v99
	v_fmamk_f32 v84, v84, 0x3e38aa3b, v36
	v_fmamk_f32 v85, v85, 0x3e38aa3b, v37
	v_fmamk_f32 v86, v86, 0x3e38aa3b, v38
	v_fmamk_f32 v87, v87, 0x3e38aa3b, v39
	v_fmamk_f32 v88, v88, 0x3e38aa3b, v32
	v_fmamk_f32 v89, v89, 0x3e38aa3b, v33
	v_fmamk_f32 v90, v90, 0x3e38aa3b, v34
	v_fmamk_f32 v91, v91, 0x3e38aa3b, v35
	v_fmamk_f32 v92, v92, 0x3e38aa3b, v28
	v_fmamk_f32 v93, v93, 0x3e38aa3b, v29
	v_fmamk_f32 v94, v94, 0x3e38aa3b, v30
	v_fmamk_f32 v95, v95, 0x3e38aa3b, v31
	v_fmamk_f32 v164, v164, 0x3e38aa3b, v24
	v_fmamk_f32 v165, v165, 0x3e38aa3b, v25
	v_fmamk_f32 v166, v166, 0x3e38aa3b, v26
	v_fmamk_f32 v167, v167, 0x3e38aa3b, v27
	v_cmp_ge_i32_e32 vcc, 0, v176
	v_cmp_ge_i32_e64 s[4:5], -1, v176
	v_cmp_ge_i32_e64 s[100:101], -2, v176
	v_cndmask_b32_e32 v84, v200, v84, vcc
	v_cndmask_b32_e64 v85, v200, v85, s[4:5]
	v_cndmask_b32_e64 v86, v200, v86, s[100:101]
	v_cmp_ge_i32_e32 vcc, -3, v176
	v_cmp_ge_i32_e64 s[4:5], 0, v177
	v_cmp_ge_i32_e64 s[100:101], -1, v177
	v_cndmask_b32_e32 v87, v200, v87, vcc
	v_cndmask_b32_e64 v88, v200, v88, s[4:5]
	v_cndmask_b32_e64 v89, v200, v89, s[100:101]
	v_cmp_ge_i32_e32 vcc, -2, v177
	v_cmp_ge_i32_e64 s[4:5], -3, v177
	v_cmp_ge_i32_e64 s[100:101], 0, v178
	v_cndmask_b32_e32 v90, v200, v90, vcc
	v_cndmask_b32_e64 v91, v200, v91, s[4:5]
	v_cndmask_b32_e64 v92, v200, v92, s[100:101]
	v_cmp_ge_i32_e32 vcc, -1, v178
	v_cmp_ge_i32_e64 s[4:5], -2, v178
	v_cmp_ge_i32_e64 s[100:101], -3, v178
	v_cndmask_b32_e32 v93, v200, v93, vcc
	v_cndmask_b32_e64 v94, v200, v94, s[4:5]
	v_cndmask_b32_e64 v95, v200, v95, s[100:101]
	v_cmp_ge_i32_e32 vcc, 0, v179
	v_cmp_ge_i32_e64 s[4:5], -1, v179
	v_cmp_ge_i32_e64 s[100:101], -2, v179
	v_cndmask_b32_e32 v164, v200, v164, vcc
	v_cndmask_b32_e64 v165, v200, v165, s[4:5]
	v_cndmask_b32_e64 v166, v200, v166, s[100:101]
	v_cmp_ge_i32_e32 vcc, -3, v179
	s_nop 1
	v_cndmask_b32_e32 v167, v200, v167, vcc
	v_add_f32_e32 v146, v72, v73
	v_add_f32_e32 v147, v74, v75
	v_add_f32_e32 v148, v76, v77
	v_add_f32_e32 v149, v78, v79
	v_add_f32_e32 v150, v80, v81
	v_add_f32_e32 v151, v82, v83
	v_add_f32_e32 v152, v96, v97
	v_add_f32_e32 v153, v98, v99
	v_add_f32_e32 v146, v146, v147
	v_add_f32_e32 v147, v148, v149
	v_add_f32_e32 v148, v150, v151
	v_add_f32_e32 v149, v152, v153
	v_add_f32_e32 v146, v146, v147
	v_add_f32_e32 v148, v148, v149
	v_add_f32_e32 v146, v146, v148
	v_exp_f32_e32 v84, v84
	v_exp_f32_e32 v85, v85
	v_exp_f32_e32 v86, v86
	v_exp_f32_e32 v87, v87
	v_exp_f32_e32 v88, v88
	v_exp_f32_e32 v89, v89
	v_exp_f32_e32 v90, v90
	v_exp_f32_e32 v91, v91
	v_exp_f32_e32 v92, v92
	v_exp_f32_e32 v93, v93
	v_exp_f32_e32 v94, v94
	v_exp_f32_e32 v95, v95
	v_exp_f32_e32 v164, v164
	v_exp_f32_e32 v165, v165
	v_exp_f32_e32 v166, v166
	v_exp_f32_e32 v167, v167
	v_add_f32_e32 v148, v84, v85
	v_add_f32_e32 v149, v86, v87
	v_add_f32_e32 v150, v88, v89
	v_add_f32_e32 v151, v90, v91
	v_add_f32_e32 v152, v92, v93
	v_add_f32_e32 v153, v94, v95
	v_add_f32_e32 v154, v164, v165
	v_add_f32_e32 v155, v166, v167
	v_add_f32_e32 v148, v148, v149
	v_add_f32_e32 v149, v150, v151
	v_add_f32_e32 v150, v152, v153
	v_add_f32_e32 v151, v154, v155
	v_add_f32_e32 v148, v148, v149
	v_add_f32_e32 v150, v150, v151
	v_add_f32_e32 v148, v148, v150
	v_max_f32_e32 v147, v146, v148
	v_cmp_lt_f32_e32 vcc, 0x69800000, v147
	s_cbranch_vccnz .Lfox2_dfallback
	v_add_f32_e32 v128, v128, v146
	v_add_f32_e32 v129, v129, v148
	v_cvt_pk_bf16_f32 v36, v72, v73
	v_cvt_pk_bf16_f32 v37, v74, v75
	v_cvt_pk_bf16_f32 v38, v76, v77
	v_cvt_pk_bf16_f32 v39, v78, v79
	v_cvt_pk_bf16_f32 v28, v80, v81
	v_cvt_pk_bf16_f32 v29, v82, v83
	v_cvt_pk_bf16_f32 v30, v96, v97
	v_cvt_pk_bf16_f32 v31, v98, v99
	s_cmp_eq_u32 s99, 0
	s_cbranch_scc1 .Lfox2_nm4
	s_barrier
